# EpiRes residual epilogues: 16 x-loads in flight per batch instead of 32 serialized load-wait-add-store
# speedup vs baseline: 1.0148x; 1.0105x over previous
;     __device__ __forceinline__ void operator()(const f32x4 (&acc)[2][2][4][2], const pg8::Unit& u, int wr, int wc, int fr, int fq) const {
;         const int row0 = u.pm * 256 + wr * 64 + fr, col0 = u.pn * 256 + wc * 32 + 4 * fq;
;         const int mi = u.pm < 64 ? (u.pm >> 3) : 8;
;         const bool split = u.nt != KT;
;         float* xb = u.pm < 64 ? XL : (XC - (size_t)ML * DM);
;         const ptrdiff_t pboff = split ? (PB + (size_t)u.part * MC * DM) - XC : 0;
;         const float* gp = gate + mi * 6144 + col0;
;         f32x4 gv[2][2];
; #pragma unroll
;         for (int bj = 0; bj < 2; ++bj)
; #pragma unroll
;             for (int n = 0; n < 2; ++n) gv[bj][n] = *(const f32x4*)(gp + bj * 128 + n * 16) * gs;
.LBB0_87:
	s_lshr_b32 s2, s16, 3
	s_cmp_lt_i32 s16, 64
	s_mulk_i32 s2, 0x1800
	s_cselect_b32 s2, s2, 0xc000
	s_cselect_b32 s5, s73, s76
	s_cselect_b32 s4, s72, s71
	s_ashr_i32 s3, s2, 31
	v_lshl_or_b32 v76, s38, 8, v160
	s_lshl_b64 s[2:3], s[2:3], 2
	s_add_u32 s2, s66, s2
	v_ashrrev_i32_e32 v77, 31, v76
	s_addc_u32 s3, s67, s3
	v_lshlrev_b64 v[152:153], 2, v[76:77]
	v_lshl_add_u64 v[76:77], s[2:3], 0, v[152:153]
	global_load_dwordx4 v[100:103], v[76:77], off
	global_load_dwordx4 v[92:95], v[76:77], off offset:64
	global_load_dwordx4 v[84:87], v[76:77], off offset:512
	s_nop 0
	global_load_dwordx4 v[76:79], v[76:77], off offset:576
	v_lshl_add_u32 v150, s16, 8, v158
	v_lshl_add_u32 v150, v150, 12, v152
	v_add_u32_e32 v151, 0x10000, v150
	v_add_u32_e32 v152, 0x20000, v150
	v_add_u32_e32 v153, 0x30000, v150
	v_add_u32_e32 v154, 0x80000, v150
	v_add_u32_e32 v155, 0x90000, v150
	v_add_u32_e32 v156, 0xa0000, v150
	v_add_u32_e32 v157, 0xb0000, v150
	s_lshl_b64 s[2:3], s[50:51], 2
	s_add_u32 s4, s4, s2
	s_addc_u32 s5, s5, s3
	s_waitcnt vmcnt(0)

;     __device__ __forceinline__ void operator()(const f32x4 (&acc)[2][2][4][2], const pg8::Unit& u, int wr, int wc, int fr, int fq) const {
;     ...
;         for (int bj = 0; bj < 2; ++bj)
; #pragma unroll
;             for (int n = 0; n < 2; ++n) gv[bj][n] = *(const f32x4*)(gp + bj * 128 + n * 16) * gs;
; #pragma unroll
;         for (int ai = 0; ai < 2; ++ai)
; #pragma unroll
;             for (int m = 0; m < 4; ++m) {
;                 float* rowp = xb + (size_t)(row0 + ai * 128 + m * 16) * DM + col0;
; #pragma unroll
;                 for (int bj = 0; bj < 2; ++bj)
; #pragma unroll
;                     for (int n = 0; n < 2; ++n) {
;                         const f32x4 v = gv[bj][n] * acc[ai][bj][m][n]; float* pe = rowp + bj * 128 + n * 16;
;                         if (split) *(f32x4*)(pe + pboff) = v;
;                         else { f32x4* p = (f32x4*)pe; *p = *p + v; }
	v_pk_mul_f32 v[142:143], v[142:143], v[102:103]
	v_pk_mul_f32 v[140:141], v[140:141], v[100:101]
	v_pk_mul_f32 v[138:139], v[138:139], v[94:95]
	v_pk_mul_f32 v[136:137], v[136:137], v[92:93]
	v_pk_mul_f32 v[134:135], v[134:135], v[86:87]
	v_pk_mul_f32 v[132:133], v[132:133], v[84:85]
	v_pk_mul_f32 v[130:131], v[130:131], v[78:79]
	v_pk_mul_f32 v[128:129], v[128:129], v[76:77]
	v_pk_mul_f32 v[126:127], v[126:127], v[102:103]
	v_pk_mul_f32 v[124:125], v[124:125], v[100:101]
	v_pk_mul_f32 v[122:123], v[122:123], v[94:95]
	v_pk_mul_f32 v[120:121], v[120:121], v[92:93]
	v_pk_mul_f32 v[118:119], v[118:119], v[86:87]
	v_pk_mul_f32 v[116:117], v[116:117], v[84:85]
	v_pk_mul_f32 v[114:115], v[114:115], v[78:79]
	v_pk_mul_f32 v[112:113], v[112:113], v[76:77]
	v_pk_mul_f32 v[110:111], v[110:111], v[102:103]
	v_pk_mul_f32 v[108:109], v[108:109], v[100:101]
	v_pk_mul_f32 v[106:107], v[106:107], v[94:95]
	v_pk_mul_f32 v[104:105], v[104:105], v[92:93]
	v_pk_mul_f32 v[98:99], v[98:99], v[86:87]
	v_pk_mul_f32 v[96:97], v[96:97], v[84:85]
	v_pk_mul_f32 v[90:91], v[90:91], v[78:79]
	v_pk_mul_f32 v[88:89], v[88:89], v[76:77]
	v_pk_mul_f32 v[82:83], v[82:83], v[102:103]
	v_pk_mul_f32 v[80:81], v[80:81], v[100:101]
	v_pk_mul_f32 v[74:75], v[74:75], v[94:95]
	v_pk_mul_f32 v[72:73], v[72:73], v[92:93]
	v_pk_mul_f32 v[70:71], v[70:71], v[86:87]
	v_pk_mul_f32 v[68:69], v[68:69], v[84:85]
	v_pk_mul_f32 v[66:67], v[66:67], v[78:79]
	v_pk_mul_f32 v[64:65], v[64:65], v[76:77]
	v_pk_mul_f32 v[62:63], v[62:63], v[102:103]
	v_pk_mul_f32 v[60:61], v[60:61], v[100:101]
	v_pk_mul_f32 v[58:59], v[58:59], v[94:95]
	v_pk_mul_f32 v[56:57], v[56:57], v[92:93]
	v_pk_mul_f32 v[54:55], v[54:55], v[86:87]
	v_pk_mul_f32 v[52:53], v[52:53], v[84:85]
	v_pk_mul_f32 v[50:51], v[50:51], v[78:79]
	v_pk_mul_f32 v[48:49], v[48:49], v[76:77]
	v_pk_mul_f32 v[46:47], v[46:47], v[102:103]
	v_pk_mul_f32 v[44:45], v[44:45], v[100:101]
	v_pk_mul_f32 v[42:43], v[42:43], v[94:95]
	v_pk_mul_f32 v[40:41], v[40:41], v[92:93]
	v_pk_mul_f32 v[38:39], v[38:39], v[86:87]
	v_pk_mul_f32 v[36:37], v[36:37], v[84:85]
	v_pk_mul_f32 v[34:35], v[34:35], v[78:79]
	v_pk_mul_f32 v[32:33], v[32:33], v[76:77]
	v_pk_mul_f32 v[30:31], v[30:31], v[102:103]
	v_pk_mul_f32 v[28:29], v[28:29], v[100:101]
	v_pk_mul_f32 v[26:27], v[26:27], v[94:95]
	v_pk_mul_f32 v[24:25], v[24:25], v[92:93]
	v_pk_mul_f32 v[22:23], v[22:23], v[86:87]
	v_pk_mul_f32 v[20:21], v[20:21], v[84:85]
	v_pk_mul_f32 v[18:19], v[18:19], v[78:79]
	v_pk_mul_f32 v[16:17], v[16:17], v[76:77]
	v_pk_mul_f32 v[14:15], v[14:15], v[102:103]
	v_pk_mul_f32 v[12:13], v[12:13], v[100:101]
	v_pk_mul_f32 v[10:11], v[10:11], v[94:95]
	v_pk_mul_f32 v[8:9], v[8:9], v[92:93]
	v_pk_mul_f32 v[6:7], v[6:7], v[86:87]
	v_pk_mul_f32 v[4:5], v[4:5], v[84:85]
	v_pk_mul_f32 v[2:3], v[2:3], v[78:79]
	v_pk_mul_f32 v[0:1], v[0:1], v[76:77]
	s_and_b64 vcc, exec, s[62:63]
	s_cbranch_vccz .Lres16_rmw

;     __device__ __forceinline__ void operator()(const f32x4 (&acc)[2][2][4][2], const pg8::Unit& u, int wr, int wc, int fr, int fq) const {
;     ...
;                 for (int bj = 0; bj < 2; ++bj)
; #pragma unroll
;                     for (int n = 0; n < 2; ++n) {
;                         const f32x4 v = gv[bj][n] * acc[ai][bj][m][n]; float* pe = rowp + bj * 128 + n * 16;
;                         if (split) *(f32x4*)(pe + pboff) = v;
;                         else { f32x4* p = (f32x4*)pe; *p = *p + v; }
	global_store_dwordx4 v150, v[140:143], s[4:5]
	global_store_dwordx4 v150, v[136:139], s[4:5] offset:64
	global_store_dwordx4 v150, v[132:135], s[4:5] offset:512
	global_store_dwordx4 v150, v[128:131], s[4:5] offset:576
	global_store_dwordx4 v151, v[124:127], s[4:5]
	global_store_dwordx4 v151, v[120:123], s[4:5] offset:64
	global_store_dwordx4 v151, v[116:119], s[4:5] offset:512
	global_store_dwordx4 v151, v[112:115], s[4:5] offset:576
	global_store_dwordx4 v152, v[108:111], s[4:5]
	global_store_dwordx4 v152, v[104:107], s[4:5] offset:64
	global_store_dwordx4 v152, v[96:99], s[4:5] offset:512
	global_store_dwordx4 v152, v[88:91], s[4:5] offset:576
	global_store_dwordx4 v153, v[80:83], s[4:5]
	global_store_dwordx4 v153, v[72:75], s[4:5] offset:64
	global_store_dwordx4 v153, v[68:71], s[4:5] offset:512
	global_store_dwordx4 v153, v[64:67], s[4:5] offset:576
	global_store_dwordx4 v154, v[60:63], s[4:5]
	global_store_dwordx4 v154, v[56:59], s[4:5] offset:64
	global_store_dwordx4 v154, v[52:55], s[4:5] offset:512
	global_store_dwordx4 v154, v[48:51], s[4:5] offset:576
	global_store_dwordx4 v155, v[44:47], s[4:5]
	global_store_dwordx4 v155, v[40:43], s[4:5] offset:64
	global_store_dwordx4 v155, v[36:39], s[4:5] offset:512
	global_store_dwordx4 v155, v[32:35], s[4:5] offset:576
	global_store_dwordx4 v156, v[28:31], s[4:5]
	global_store_dwordx4 v156, v[24:27], s[4:5] offset:64
	global_store_dwordx4 v156, v[20:23], s[4:5] offset:512
	global_store_dwordx4 v156, v[16:19], s[4:5] offset:576
	global_store_dwordx4 v157, v[12:15], s[4:5]
	global_store_dwordx4 v157, v[8:11], s[4:5] offset:64
	global_store_dwordx4 v157, v[4:7], s[4:5] offset:512
	global_store_dwordx4 v157, v[0:3], s[4:5] offset:576
	s_branch .Lres16_done
.Lres16_rmw:
	global_load_dwordx4 v[162:165], v150, s[4:5]
	global_load_dwordx4 v[166:169], v150, s[4:5] offset:64
	global_load_dwordx4 v[170:173], v150, s[4:5] offset:512
	global_load_dwordx4 v[174:177], v150, s[4:5] offset:576
	global_load_dwordx4 v[184:187], v151, s[4:5]
	global_load_dwordx4 v[188:191], v151, s[4:5] offset:64
	global_load_dwordx4 v[204:207], v151, s[4:5] offset:512
	global_load_dwordx4 v[210:213], v151, s[4:5] offset:576
	global_load_dwordx4 v[214:217], v152, s[4:5]
	global_load_dwordx4 v[218:221], v152, s[4:5] offset:64
	global_load_dwordx4 v[222:225], v152, s[4:5] offset:512
	global_load_dwordx4 v[228:231], v152, s[4:5] offset:576
	global_load_dwordx4 v[232:235], v153, s[4:5]
	global_load_dwordx4 v[236:239], v153, s[4:5] offset:64
	global_load_dwordx4 v[240:243], v153, s[4:5] offset:512
	global_load_dwordx4 v[244:247], v153, s[4:5] offset:576
	s_waitcnt vmcnt(15)
	v_pk_add_f32 v[142:143], v[142:143], v[164:165]
	v_pk_add_f32 v[140:141], v[140:141], v[162:163]

;     __device__ __forceinline__ void operator()(const f32x4 (&acc)[2][2][4][2], const pg8::Unit& u, int wr, int wc, int fr, int fq) const {
;     ...
;                         const f32x4 v = gv[bj][n] * acc[ai][bj][m][n]; float* pe = rowp + bj * 128 + n * 16;
;                         if (split) *(f32x4*)(pe + pboff) = v;
;                         else { f32x4* p = (f32x4*)pe; *p = *p + v; }
	global_store_dwordx4 v150, v[140:143], s[4:5]
	s_waitcnt vmcnt(15)
	v_pk_add_f32 v[138:139], v[138:139], v[168:169]
	v_pk_add_f32 v[136:137], v[136:137], v[166:167]

;     __device__ __forceinline__ void operator()(const f32x4 (&acc)[2][2][4][2], const pg8::Unit& u, int wr, int wc, int fr, int fq) const {
;     ...
;                         const f32x4 v = gv[bj][n] * acc[ai][bj][m][n]; float* pe = rowp + bj * 128 + n * 16;
;                         if (split) *(f32x4*)(pe + pboff) = v;
;                         else { f32x4* p = (f32x4*)pe; *p = *p + v; }
	global_store_dwordx4 v150, v[136:139], s[4:5] offset:64
	s_waitcnt vmcnt(15)
	v_pk_add_f32 v[134:135], v[134:135], v[172:173]
	v_pk_add_f32 v[132:133], v[132:133], v[170:171]

;     __device__ __forceinline__ void operator()(const f32x4 (&acc)[2][2][4][2], const pg8::Unit& u, int wr, int wc, int fr, int fq) const {
;     ...
;                         const f32x4 v = gv[bj][n] * acc[ai][bj][m][n]; float* pe = rowp + bj * 128 + n * 16;
;                         if (split) *(f32x4*)(pe + pboff) = v;
;                         else { f32x4* p = (f32x4*)pe; *p = *p + v; }
	global_store_dwordx4 v150, v[132:135], s[4:5] offset:512
	s_waitcnt vmcnt(15)
	v_pk_add_f32 v[130:131], v[130:131], v[176:177]
	v_pk_add_f32 v[128:129], v[128:129], v[174:175]

;     __device__ __forceinline__ void operator()(const f32x4 (&acc)[2][2][4][2], const pg8::Unit& u, int wr, int wc, int fr, int fq) const {
;     ...
;                         const f32x4 v = gv[bj][n] * acc[ai][bj][m][n]; float* pe = rowp + bj * 128 + n * 16;
;                         if (split) *(f32x4*)(pe + pboff) = v;
;                         else { f32x4* p = (f32x4*)pe; *p = *p + v; }
	global_store_dwordx4 v150, v[128:131], s[4:5] offset:576
	s_waitcnt vmcnt(15)
	v_pk_add_f32 v[126:127], v[126:127], v[186:187]
	v_pk_add_f32 v[124:125], v[124:125], v[184:185]

;     __device__ __forceinline__ void operator()(const f32x4 (&acc)[2][2][4][2], const pg8::Unit& u, int wr, int wc, int fr, int fq) const {
;     ...
;                         const f32x4 v = gv[bj][n] * acc[ai][bj][m][n]; float* pe = rowp + bj * 128 + n * 16;
;                         if (split) *(f32x4*)(pe + pboff) = v;
;                         else { f32x4* p = (f32x4*)pe; *p = *p + v; }
	global_store_dwordx4 v151, v[124:127], s[4:5]
	s_waitcnt vmcnt(15)
	v_pk_add_f32 v[122:123], v[122:123], v[190:191]
	v_pk_add_f32 v[120:121], v[120:121], v[188:189]

;     __device__ __forceinline__ void operator()(const f32x4 (&acc)[2][2][4][2], const pg8::Unit& u, int wr, int wc, int fr, int fq) const {
;     ...
;                         const f32x4 v = gv[bj][n] * acc[ai][bj][m][n]; float* pe = rowp + bj * 128 + n * 16;
;                         if (split) *(f32x4*)(pe + pboff) = v;
;                         else { f32x4* p = (f32x4*)pe; *p = *p + v; }
	global_store_dwordx4 v151, v[120:123], s[4:5] offset:64
	s_waitcnt vmcnt(15)
	v_pk_add_f32 v[118:119], v[118:119], v[206:207]
	v_pk_add_f32 v[116:117], v[116:117], v[204:205]

;     __device__ __forceinline__ void operator()(const f32x4 (&acc)[2][2][4][2], const pg8::Unit& u, int wr, int wc, int fr, int fq) const {
;     ...
;                         const f32x4 v = gv[bj][n] * acc[ai][bj][m][n]; float* pe = rowp + bj * 128 + n * 16;
;                         if (split) *(f32x4*)(pe + pboff) = v;
;                         else { f32x4* p = (f32x4*)pe; *p = *p + v; }
	global_store_dwordx4 v151, v[116:119], s[4:5] offset:512
	s_waitcnt vmcnt(15)
	v_pk_add_f32 v[114:115], v[114:115], v[212:213]
	v_pk_add_f32 v[112:113], v[112:113], v[210:211]

;     __device__ __forceinline__ void operator()(const f32x4 (&acc)[2][2][4][2], const pg8::Unit& u, int wr, int wc, int fr, int fq) const {
;     ...
;                         const f32x4 v = gv[bj][n] * acc[ai][bj][m][n]; float* pe = rowp + bj * 128 + n * 16;
;                         if (split) *(f32x4*)(pe + pboff) = v;
;                         else { f32x4* p = (f32x4*)pe; *p = *p + v; }
	global_store_dwordx4 v151, v[112:115], s[4:5] offset:576
	s_waitcnt vmcnt(15)
	v_pk_add_f32 v[110:111], v[110:111], v[216:217]
	v_pk_add_f32 v[108:109], v[108:109], v[214:215]

;     __device__ __forceinline__ void operator()(const f32x4 (&acc)[2][2][4][2], const pg8::Unit& u, int wr, int wc, int fr, int fq) const {
;     ...
;                         const f32x4 v = gv[bj][n] * acc[ai][bj][m][n]; float* pe = rowp + bj * 128 + n * 16;
;                         if (split) *(f32x4*)(pe + pboff) = v;
;                         else { f32x4* p = (f32x4*)pe; *p = *p + v; }
	global_store_dwordx4 v152, v[108:111], s[4:5]
	s_waitcnt vmcnt(15)
	v_pk_add_f32 v[106:107], v[106:107], v[220:221]
	v_pk_add_f32 v[104:105], v[104:105], v[218:219]

;     __device__ __forceinline__ void operator()(const f32x4 (&acc)[2][2][4][2], const pg8::Unit& u, int wr, int wc, int fr, int fq) const {
;     ...
;                         const f32x4 v = gv[bj][n] * acc[ai][bj][m][n]; float* pe = rowp + bj * 128 + n * 16;
;                         if (split) *(f32x4*)(pe + pboff) = v;
;                         else { f32x4* p = (f32x4*)pe; *p = *p + v; }
	global_store_dwordx4 v152, v[104:107], s[4:5] offset:64
	s_waitcnt vmcnt(15)
	v_pk_add_f32 v[98:99], v[98:99], v[224:225]
	v_pk_add_f32 v[96:97], v[96:97], v[222:223]

;     __device__ __forceinline__ void operator()(const f32x4 (&acc)[2][2][4][2], const pg8::Unit& u, int wr, int wc, int fr, int fq) const {
;     ...
;                         const f32x4 v = gv[bj][n] * acc[ai][bj][m][n]; float* pe = rowp + bj * 128 + n * 16;
;                         if (split) *(f32x4*)(pe + pboff) = v;
;                         else { f32x4* p = (f32x4*)pe; *p = *p + v; }
	global_store_dwordx4 v152, v[96:99], s[4:5] offset:512
	s_waitcnt vmcnt(15)
	v_pk_add_f32 v[90:91], v[90:91], v[230:231]
	v_pk_add_f32 v[88:89], v[88:89], v[228:229]

;     __device__ __forceinline__ void operator()(const f32x4 (&acc)[2][2][4][2], const pg8::Unit& u, int wr, int wc, int fr, int fq) const {
;     ...
;                         const f32x4 v = gv[bj][n] * acc[ai][bj][m][n]; float* pe = rowp + bj * 128 + n * 16;
;                         if (split) *(f32x4*)(pe + pboff) = v;
;                         else { f32x4* p = (f32x4*)pe; *p = *p + v; }
	global_store_dwordx4 v152, v[88:91], s[4:5] offset:576
	s_waitcnt vmcnt(15)
	v_pk_add_f32 v[82:83], v[82:83], v[234:235]
	v_pk_add_f32 v[80:81], v[80:81], v[232:233]

;     __device__ __forceinline__ void operator()(const f32x4 (&acc)[2][2][4][2], const pg8::Unit& u, int wr, int wc, int fr, int fq) const {
;     ...
;                         const f32x4 v = gv[bj][n] * acc[ai][bj][m][n]; float* pe = rowp + bj * 128 + n * 16;
;                         if (split) *(f32x4*)(pe + pboff) = v;
;                         else { f32x4* p = (f32x4*)pe; *p = *p + v; }
	global_store_dwordx4 v153, v[80:83], s[4:5]
	s_waitcnt vmcnt(15)
	v_pk_add_f32 v[74:75], v[74:75], v[238:239]
	v_pk_add_f32 v[72:73], v[72:73], v[236:237]

;     __device__ __forceinline__ void operator()(const f32x4 (&acc)[2][2][4][2], const pg8::Unit& u, int wr, int wc, int fr, int fq) const {
;     ...
;                         const f32x4 v = gv[bj][n] * acc[ai][bj][m][n]; float* pe = rowp + bj * 128 + n * 16;
;                         if (split) *(f32x4*)(pe + pboff) = v;
;                         else { f32x4* p = (f32x4*)pe; *p = *p + v; }
	global_store_dwordx4 v153, v[72:75], s[4:5] offset:64
	s_waitcnt vmcnt(15)
	v_pk_add_f32 v[70:71], v[70:71], v[242:243]
	v_pk_add_f32 v[68:69], v[68:69], v[240:241]

;     __device__ __forceinline__ void operator()(const f32x4 (&acc)[2][2][4][2], const pg8::Unit& u, int wr, int wc, int fr, int fq) const {
;     ...
;                         const f32x4 v = gv[bj][n] * acc[ai][bj][m][n]; float* pe = rowp + bj * 128 + n * 16;
;                         if (split) *(f32x4*)(pe + pboff) = v;
;                         else { f32x4* p = (f32x4*)pe; *p = *p + v; }
	global_store_dwordx4 v153, v[68:71], s[4:5] offset:512
	s_waitcnt vmcnt(15)
	v_pk_add_f32 v[66:67], v[66:67], v[246:247]
	v_pk_add_f32 v[64:65], v[64:65], v[244:245]

;     __device__ __forceinline__ void operator()(const f32x4 (&acc)[2][2][4][2], const pg8::Unit& u, int wr, int wc, int fr, int fq) const {
;     ...
;                         const f32x4 v = gv[bj][n] * acc[ai][bj][m][n]; float* pe = rowp + bj * 128 + n * 16;
;                         if (split) *(f32x4*)(pe + pboff) = v;
;                         else { f32x4* p = (f32x4*)pe; *p = *p + v; }
	global_store_dwordx4 v153, v[64:67], s[4:5] offset:576
	global_load_dwordx4 v[162:165], v154, s[4:5]
	global_load_dwordx4 v[166:169], v154, s[4:5] offset:64
	global_load_dwordx4 v[170:173], v154, s[4:5] offset:512
	global_load_dwordx4 v[174:177], v154, s[4:5] offset:576
	global_load_dwordx4 v[184:187], v155, s[4:5]
	global_load_dwordx4 v[188:191], v155, s[4:5] offset:64
	global_load_dwordx4 v[204:207], v155, s[4:5] offset:512
	global_load_dwordx4 v[210:213], v155, s[4:5] offset:576
	global_load_dwordx4 v[214:217], v156, s[4:5]
	global_load_dwordx4 v[218:221], v156, s[4:5] offset:64
	global_load_dwordx4 v[222:225], v156, s[4:5] offset:512
	global_load_dwordx4 v[228:231], v156, s[4:5] offset:576
	global_load_dwordx4 v[232:235], v157, s[4:5]
	global_load_dwordx4 v[236:239], v157, s[4:5] offset:64
	global_load_dwordx4 v[240:243], v157, s[4:5] offset:512
	global_load_dwordx4 v[244:247], v157, s[4:5] offset:576
	s_waitcnt vmcnt(15)
	v_pk_add_f32 v[62:63], v[62:63], v[164:165]
	v_pk_add_f32 v[60:61], v[60:61], v[162:163]

;     __device__ __forceinline__ void operator()(const f32x4 (&acc)[2][2][4][2], const pg8::Unit& u, int wr, int wc, int fr, int fq) const {
;     ...
;                         const f32x4 v = gv[bj][n] * acc[ai][bj][m][n]; float* pe = rowp + bj * 128 + n * 16;
;                         if (split) *(f32x4*)(pe + pboff) = v;
;                         else { f32x4* p = (f32x4*)pe; *p = *p + v; }
	global_store_dwordx4 v154, v[60:63], s[4:5]
	s_waitcnt vmcnt(15)
	v_pk_add_f32 v[58:59], v[58:59], v[168:169]
	v_pk_add_f32 v[56:57], v[56:57], v[166:167]

;     __device__ __forceinline__ void operator()(const f32x4 (&acc)[2][2][4][2], const pg8::Unit& u, int wr, int wc, int fr, int fq) const {
;     ...
;                         const f32x4 v = gv[bj][n] * acc[ai][bj][m][n]; float* pe = rowp + bj * 128 + n * 16;
;                         if (split) *(f32x4*)(pe + pboff) = v;
;                         else { f32x4* p = (f32x4*)pe; *p = *p + v; }
	global_store_dwordx4 v154, v[56:59], s[4:5] offset:64
	s_waitcnt vmcnt(15)
	v_pk_add_f32 v[54:55], v[54:55], v[172:173]
	v_pk_add_f32 v[52:53], v[52:53], v[170:171]

;     __device__ __forceinline__ void operator()(const f32x4 (&acc)[2][2][4][2], const pg8::Unit& u, int wr, int wc, int fr, int fq) const {
;     ...
;                         const f32x4 v = gv[bj][n] * acc[ai][bj][m][n]; float* pe = rowp + bj * 128 + n * 16;
;                         if (split) *(f32x4*)(pe + pboff) = v;
;                         else { f32x4* p = (f32x4*)pe; *p = *p + v; }
	global_store_dwordx4 v154, v[52:55], s[4:5] offset:512
	s_waitcnt vmcnt(15)
	v_pk_add_f32 v[50:51], v[50:51], v[176:177]
	v_pk_add_f32 v[48:49], v[48:49], v[174:175]

;     __device__ __forceinline__ void operator()(const f32x4 (&acc)[2][2][4][2], const pg8::Unit& u, int wr, int wc, int fr, int fq) const {
;     ...
;                         const f32x4 v = gv[bj][n] * acc[ai][bj][m][n]; float* pe = rowp + bj * 128 + n * 16;
;                         if (split) *(f32x4*)(pe + pboff) = v;
;                         else { f32x4* p = (f32x4*)pe; *p = *p + v; }
	global_store_dwordx4 v154, v[48:51], s[4:5] offset:576
	s_waitcnt vmcnt(15)
	v_pk_add_f32 v[46:47], v[46:47], v[186:187]
	v_pk_add_f32 v[44:45], v[44:45], v[184:185]

;     __device__ __forceinline__ void operator()(const f32x4 (&acc)[2][2][4][2], const pg8::Unit& u, int wr, int wc, int fr, int fq) const {
;     ...
;                         const f32x4 v = gv[bj][n] * acc[ai][bj][m][n]; float* pe = rowp + bj * 128 + n * 16;
;                         if (split) *(f32x4*)(pe + pboff) = v;
;                         else { f32x4* p = (f32x4*)pe; *p = *p + v; }
	global_store_dwordx4 v155, v[44:47], s[4:5]
	s_waitcnt vmcnt(15)
	v_pk_add_f32 v[42:43], v[42:43], v[190:191]
	v_pk_add_f32 v[40:41], v[40:41], v[188:189]

;     __device__ __forceinline__ void operator()(const f32x4 (&acc)[2][2][4][2], const pg8::Unit& u, int wr, int wc, int fr, int fq) const {
;     ...
;                         const f32x4 v = gv[bj][n] * acc[ai][bj][m][n]; float* pe = rowp + bj * 128 + n * 16;
;                         if (split) *(f32x4*)(pe + pboff) = v;
;                         else { f32x4* p = (f32x4*)pe; *p = *p + v; }
	global_store_dwordx4 v155, v[40:43], s[4:5] offset:64
	s_waitcnt vmcnt(15)
	v_pk_add_f32 v[38:39], v[38:39], v[206:207]
	v_pk_add_f32 v[36:37], v[36:37], v[204:205]

;     __device__ __forceinline__ void operator()(const f32x4 (&acc)[2][2][4][2], const pg8::Unit& u, int wr, int wc, int fr, int fq) const {
;     ...
;                         const f32x4 v = gv[bj][n] * acc[ai][bj][m][n]; float* pe = rowp + bj * 128 + n * 16;
;                         if (split) *(f32x4*)(pe + pboff) = v;
;                         else { f32x4* p = (f32x4*)pe; *p = *p + v; }
	global_store_dwordx4 v155, v[36:39], s[4:5] offset:512
	s_waitcnt vmcnt(15)
	v_pk_add_f32 v[34:35], v[34:35], v[212:213]
	v_pk_add_f32 v[32:33], v[32:33], v[210:211]

;     __device__ __forceinline__ void operator()(const f32x4 (&acc)[2][2][4][2], const pg8::Unit& u, int wr, int wc, int fr, int fq) const {
;     ...
;                         const f32x4 v = gv[bj][n] * acc[ai][bj][m][n]; float* pe = rowp + bj * 128 + n * 16;
;                         if (split) *(f32x4*)(pe + pboff) = v;
;                         else { f32x4* p = (f32x4*)pe; *p = *p + v; }
	global_store_dwordx4 v155, v[32:35], s[4:5] offset:576
	s_waitcnt vmcnt(15)
	v_pk_add_f32 v[30:31], v[30:31], v[216:217]
	v_pk_add_f32 v[28:29], v[28:29], v[214:215]

;     __device__ __forceinline__ void operator()(const f32x4 (&acc)[2][2][4][2], const pg8::Unit& u, int wr, int wc, int fr, int fq) const {
;     ...
;                         const f32x4 v = gv[bj][n] * acc[ai][bj][m][n]; float* pe = rowp + bj * 128 + n * 16;
;                         if (split) *(f32x4*)(pe + pboff) = v;
;                         else { f32x4* p = (f32x4*)pe; *p = *p + v; }
	global_store_dwordx4 v156, v[28:31], s[4:5]
	s_waitcnt vmcnt(15)
	v_pk_add_f32 v[26:27], v[26:27], v[220:221]
	v_pk_add_f32 v[24:25], v[24:25], v[218:219]

;     __device__ __forceinline__ void operator()(const f32x4 (&acc)[2][2][4][2], const pg8::Unit& u, int wr, int wc, int fr, int fq) const {
;     ...
;                         const f32x4 v = gv[bj][n] * acc[ai][bj][m][n]; float* pe = rowp + bj * 128 + n * 16;
;                         if (split) *(f32x4*)(pe + pboff) = v;
;                         else { f32x4* p = (f32x4*)pe; *p = *p + v; }
	global_store_dwordx4 v156, v[24:27], s[4:5] offset:64
	s_waitcnt vmcnt(15)
	v_pk_add_f32 v[22:23], v[22:23], v[224:225]
	v_pk_add_f32 v[20:21], v[20:21], v[222:223]

;     __device__ __forceinline__ void operator()(const f32x4 (&acc)[2][2][4][2], const pg8::Unit& u, int wr, int wc, int fr, int fq) const {
;     ...
;                         const f32x4 v = gv[bj][n] * acc[ai][bj][m][n]; float* pe = rowp + bj * 128 + n * 16;
;                         if (split) *(f32x4*)(pe + pboff) = v;
;                         else { f32x4* p = (f32x4*)pe; *p = *p + v; }
	global_store_dwordx4 v156, v[20:23], s[4:5] offset:512
	s_waitcnt vmcnt(15)
	v_pk_add_f32 v[18:19], v[18:19], v[230:231]
	v_pk_add_f32 v[16:17], v[16:17], v[228:229]

;     __device__ __forceinline__ void operator()(const f32x4 (&acc)[2][2][4][2], const pg8::Unit& u, int wr, int wc, int fr, int fq) const {
;     ...
;                         const f32x4 v = gv[bj][n] * acc[ai][bj][m][n]; float* pe = rowp + bj * 128 + n * 16;
;                         if (split) *(f32x4*)(pe + pboff) = v;
;                         else { f32x4* p = (f32x4*)pe; *p = *p + v; }
	global_store_dwordx4 v156, v[16:19], s[4:5] offset:576
	s_waitcnt vmcnt(15)
	v_pk_add_f32 v[14:15], v[14:15], v[234:235]
	v_pk_add_f32 v[12:13], v[12:13], v[232:233]

;     __device__ __forceinline__ void operator()(const f32x4 (&acc)[2][2][4][2], const pg8::Unit& u, int wr, int wc, int fr, int fq) const {
;     ...
;                         const f32x4 v = gv[bj][n] * acc[ai][bj][m][n]; float* pe = rowp + bj * 128 + n * 16;
;                         if (split) *(f32x4*)(pe + pboff) = v;
;                         else { f32x4* p = (f32x4*)pe; *p = *p + v; }
	global_store_dwordx4 v157, v[12:15], s[4:5]
	s_waitcnt vmcnt(15)
	v_pk_add_f32 v[10:11], v[10:11], v[238:239]
	v_pk_add_f32 v[8:9], v[8:9], v[236:237]

;     __device__ __forceinline__ void operator()(const f32x4 (&acc)[2][2][4][2], const pg8::Unit& u, int wr, int wc, int fr, int fq) const {
;     ...
;                         const f32x4 v = gv[bj][n] * acc[ai][bj][m][n]; float* pe = rowp + bj * 128 + n * 16;
;                         if (split) *(f32x4*)(pe + pboff) = v;
;                         else { f32x4* p = (f32x4*)pe; *p = *p + v; }
	global_store_dwordx4 v157, v[8:11], s[4:5] offset:64
	s_waitcnt vmcnt(15)
	v_pk_add_f32 v[6:7], v[6:7], v[242:243]
	v_pk_add_f32 v[4:5], v[4:5], v[240:241]

;     __device__ __forceinline__ void operator()(const f32x4 (&acc)[2][2][4][2], const pg8::Unit& u, int wr, int wc, int fr, int fq) const {
;     ...
;                         const f32x4 v = gv[bj][n] * acc[ai][bj][m][n]; float* pe = rowp + bj * 128 + n * 16;
;                         if (split) *(f32x4*)(pe + pboff) = v;
;                         else { f32x4* p = (f32x4*)pe; *p = *p + v; }
	global_store_dwordx4 v157, v[4:7], s[4:5] offset:512
	s_waitcnt vmcnt(15)
	v_pk_add_f32 v[2:3], v[2:3], v[246:247]
	v_pk_add_f32 v[0:1], v[0:1], v[244:245]

; #define PG8_BAR __builtin_amdgcn_s_barrier()
; template <class Epi, class Sched, bool ALIGN_EPI = false, bool SP2 = false>
; __device__ __forceinline__ void gemm_phase(PG8_LAS unsigned char* lds, const Gemm g, const Sched& S, const Epi& E) {
;     ...
;         if constexpr (ALIGN_EPI) { if (wr == 0) PG8_BAR; }
;         if constexpr (!Epi::AFTER_DRAIN) { E(acc, cur, wr, wc, fr, fq); S.done(cur); }
;         if (!has_next) break;
; #pragma unroll
;         for (int a = 0; a < 2; ++a)
; #pragma unroll
;             for (int b = 0; b < 2; ++b)
; #pragma unroll
;                 for (int m = 0; m < 4; ++m)
; #pragma unroll
;                     for (int n = 0; n < 2; ++n) acc[a][b][m][n] = (f32x4){0.f, 0.f, 0.f, 0.f};
;         cur = nxt; cA = nA; cB = nB; ++ui;
;         if constexpr (ALIGN_EPI) { if (wr == 1) PG8_BAR; }
;     __device__ __forceinline__ void operator()(const f32x4 (&acc)[2][2][4][2], const pg8::Unit& u, int wr, int wc, int fr, int fq) const {
;     ...
;                         const f32x4 v = gv[bj][n] * acc[ai][bj][m][n]; float* pe = rowp + bj * 128 + n * 16;
;                         if (split) *(f32x4*)(pe + pboff) = v;
;                         else { f32x4* p = (f32x4*)pe; *p = *p + v; }
	global_store_dwordx4 v157, v[0:3], s[4:5] offset:576
.Lres16_done:
	s_andn2_b64 vcc, exec, s[56:57]
	s_mov_b64 s[2:3], -1
	s_cbranch_vccnz .LBB0_75
.LBB0_216:
	s_andn2_b64 vcc, exec, s[40:41]
	s_cbranch_vccnz .LBB0_74
	s_barrier
	s_branch .LBB0_74

; #define PG8_BAR __builtin_amdgcn_s_barrier()
; template <class Epi, class Sched, bool ALIGN_EPI = false, bool SP2 = false>
; __device__ __forceinline__ void gemm_phase(PG8_LAS unsigned char* lds, const Gemm g, const Sched& S, const Epi& E) {
;     ...
;         if constexpr (ALIGN_EPI) { if (wr == 0) PG8_BAR; }
;         if constexpr (!Epi::AFTER_DRAIN) { E(acc, cur, wr, wc, fr, fq); S.done(cur); }
;         if (!has_next) break;
; #pragma unroll
;         for (int a = 0; a < 2; ++a)
; #pragma unroll
;             for (int b = 0; b < 2; ++b)
; #pragma unroll
;                 for (int m = 0; m < 4; ++m)
; #pragma unroll
;                     for (int n = 0; n < 2; ++n) acc[a][b][m][n] = (f32x4){0.f, 0.f, 0.f, 0.f};
;         cur = nxt; cA = nA; cB = nB; ++ui;
;         if constexpr (ALIGN_EPI) { if (wr == 1) PG8_BAR; }
;     __device__ __forceinline__ void operator()(const f32x4 (&acc)[2][2][4][2], const pg8::Unit& u, int wr, int wc, int fr, int fq) const {
;     ...
;                         const f32x4 v = gv[bj][n] * acc[ai][bj][m][n]; float* pe = rowp + bj * 128 + n * 16;
;                         if (split) *(f32x4*)(pe + pboff) = v;
;                         else { f32x4* p = (f32x4*)pe; *p = *p + v; }
.Lres32_done:
	s_andn2_b64 vcc, exec, s[56:57]
	s_mov_b64 s[2:3], -1
	s_cbranch_vccnz .LBB0_231
.LBB0_372:
	s_andn2_b64 vcc, exec, s[40:41]
	s_cbranch_vccnz .LBB0_230
	s_barrier
	s_branch .LBB0_230

;     __device__ __forceinline__ void operator()(const f32x4 (&acc)[2][2][4][2], const pg8::Unit& u, int wr, int wc, int fr, int fq) const {
;         const int row0 = u.pm * 256 + wr * 64 + fr, col0 = u.pn * 256 + wc * 32 + 4 * fq;
;         const int mi = u.pm < 64 ? (u.pm >> 3) : 8;
;         const bool split = u.nt != KT;
;         float* xb = u.pm < 64 ? XL : (XC - (size_t)ML * DM);
;         const ptrdiff_t pboff = split ? (PB + (size_t)u.part * MC * DM) - XC : 0;
;         const float* gp = gate + mi * 6144 + col0;
;         f32x4 gv[2][2];
; #pragma unroll
;         for (int bj = 0; bj < 2; ++bj)
; #pragma unroll
;             for (int n = 0; n < 2; ++n) gv[bj][n] = *(const f32x4*)(gp + bj * 128 + n * 16) * gs;
.LBB0_912:
	s_lshr_b32 s2, s80, 3
	s_cmp_lt_i32 s80, 64
	s_mulk_i32 s2, 0x1800
	s_cselect_b32 s2, s2, 0xc000
	v_lshl_or_b32 v76, s4, 8, v160
	s_cselect_b32 s5, s73, s70
	s_cselect_b32 s4, s72, s69
	s_ashr_i32 s3, s2, 31
	s_lshl_b64 s[2:3], s[2:3], 2
	s_add_u32 s2, s67, s2
	v_ashrrev_i32_e32 v77, 31, v76
	s_addc_u32 s3, s68, s3
	v_lshlrev_b64 v[152:153], 2, v[76:77]
	v_lshl_add_u64 v[76:77], s[2:3], 0, v[152:153]
	global_load_dwordx4 v[100:103], v[76:77], off
	global_load_dwordx4 v[92:95], v[76:77], off offset:64
	global_load_dwordx4 v[84:87], v[76:77], off offset:512
	s_nop 0
	global_load_dwordx4 v[76:79], v[76:77], off offset:576
	v_lshl_add_u32 v150, s80, 8, v158
	v_lshl_add_u32 v150, v150, 12, v152
	v_add_u32_e32 v151, 0x10000, v150
	v_add_u32_e32 v152, 0x20000, v150
	v_add_u32_e32 v153, 0x30000, v150
	v_add_u32_e32 v154, 0x80000, v150
	v_add_u32_e32 v155, 0x90000, v150
	v_add_u32_e32 v156, 0xa0000, v150
	v_add_u32_e32 v157, 0xb0000, v150
	s_lshl_b64 s[2:3], s[50:51], 2
	s_add_u32 s4, s4, s2
	s_addc_u32 s5, s5, s3
	s_waitcnt vmcnt(0)

;     __device__ __forceinline__ void operator()(const f32x4 (&acc)[2][2][4][2], const pg8::Unit& u, int wr, int wc, int fr, int fq) const {
;     ...
;         for (int bj = 0; bj < 2; ++bj)
; #pragma unroll
;             for (int n = 0; n < 2; ++n) gv[bj][n] = *(const f32x4*)(gp + bj * 128 + n * 16) * gs;
; #pragma unroll
;         for (int ai = 0; ai < 2; ++ai)
; #pragma unroll
;             for (int m = 0; m < 4; ++m) {
;                 float* rowp = xb + (size_t)(row0 + ai * 128 + m * 16) * DM + col0;
; #pragma unroll
;                 for (int bj = 0; bj < 2; ++bj)
; #pragma unroll
;                     for (int n = 0; n < 2; ++n) {
;                         const f32x4 v = gv[bj][n] * acc[ai][bj][m][n]; float* pe = rowp + bj * 128 + n * 16;
;                         if (split) *(f32x4*)(pe + pboff) = v;
;                         else { f32x4* p = (f32x4*)pe; *p = *p + v; }
	v_pk_mul_f32 v[142:143], v[142:143], v[102:103]
	v_pk_mul_f32 v[140:141], v[140:141], v[100:101]
	v_pk_mul_f32 v[138:139], v[138:139], v[94:95]
	v_pk_mul_f32 v[136:137], v[136:137], v[92:93]
	v_pk_mul_f32 v[134:135], v[134:135], v[86:87]
	v_pk_mul_f32 v[132:133], v[132:133], v[84:85]
	v_pk_mul_f32 v[130:131], v[130:131], v[78:79]
	v_pk_mul_f32 v[128:129], v[128:129], v[76:77]
	v_pk_mul_f32 v[126:127], v[126:127], v[102:103]
	v_pk_mul_f32 v[124:125], v[124:125], v[100:101]
	v_pk_mul_f32 v[122:123], v[122:123], v[94:95]
	v_pk_mul_f32 v[120:121], v[120:121], v[92:93]
	v_pk_mul_f32 v[118:119], v[118:119], v[86:87]
	v_pk_mul_f32 v[116:117], v[116:117], v[84:85]
	v_pk_mul_f32 v[114:115], v[114:115], v[78:79]
	v_pk_mul_f32 v[112:113], v[112:113], v[76:77]
	v_pk_mul_f32 v[110:111], v[110:111], v[102:103]
	v_pk_mul_f32 v[108:109], v[108:109], v[100:101]
	v_pk_mul_f32 v[106:107], v[106:107], v[94:95]
	v_pk_mul_f32 v[104:105], v[104:105], v[92:93]
	v_pk_mul_f32 v[98:99], v[98:99], v[86:87]
	v_pk_mul_f32 v[96:97], v[96:97], v[84:85]
	v_pk_mul_f32 v[90:91], v[90:91], v[78:79]
	v_pk_mul_f32 v[88:89], v[88:89], v[76:77]
	v_pk_mul_f32 v[82:83], v[82:83], v[102:103]
	v_pk_mul_f32 v[80:81], v[80:81], v[100:101]
	v_pk_mul_f32 v[74:75], v[74:75], v[94:95]
	v_pk_mul_f32 v[72:73], v[72:73], v[92:93]
	v_pk_mul_f32 v[70:71], v[70:71], v[86:87]
	v_pk_mul_f32 v[68:69], v[68:69], v[84:85]
	v_pk_mul_f32 v[66:67], v[66:67], v[78:79]
	v_pk_mul_f32 v[64:65], v[64:65], v[76:77]
	v_pk_mul_f32 v[62:63], v[62:63], v[102:103]
	v_pk_mul_f32 v[60:61], v[60:61], v[100:101]
	v_pk_mul_f32 v[58:59], v[58:59], v[94:95]
	v_pk_mul_f32 v[56:57], v[56:57], v[92:93]
	v_pk_mul_f32 v[54:55], v[54:55], v[86:87]
	v_pk_mul_f32 v[52:53], v[52:53], v[84:85]
	v_pk_mul_f32 v[50:51], v[50:51], v[78:79]
	v_pk_mul_f32 v[48:49], v[48:49], v[76:77]
	v_pk_mul_f32 v[46:47], v[46:47], v[102:103]
	v_pk_mul_f32 v[44:45], v[44:45], v[100:101]
	v_pk_mul_f32 v[42:43], v[42:43], v[94:95]
	v_pk_mul_f32 v[40:41], v[40:41], v[92:93]
	v_pk_mul_f32 v[38:39], v[38:39], v[86:87]
	v_pk_mul_f32 v[36:37], v[36:37], v[84:85]
	v_pk_mul_f32 v[34:35], v[34:35], v[78:79]
	v_pk_mul_f32 v[32:33], v[32:33], v[76:77]
	v_pk_mul_f32 v[30:31], v[30:31], v[102:103]
	v_pk_mul_f32 v[28:29], v[28:29], v[100:101]
	v_pk_mul_f32 v[26:27], v[26:27], v[94:95]
	v_pk_mul_f32 v[24:25], v[24:25], v[92:93]
	v_pk_mul_f32 v[22:23], v[22:23], v[86:87]
	v_pk_mul_f32 v[20:21], v[20:21], v[84:85]
	v_pk_mul_f32 v[18:19], v[18:19], v[78:79]
	v_pk_mul_f32 v[16:17], v[16:17], v[76:77]
	v_pk_mul_f32 v[14:15], v[14:15], v[102:103]
	v_pk_mul_f32 v[12:13], v[12:13], v[100:101]
	v_pk_mul_f32 v[10:11], v[10:11], v[94:95]
	v_pk_mul_f32 v[8:9], v[8:9], v[92:93]
	v_pk_mul_f32 v[6:7], v[6:7], v[86:87]
	v_pk_mul_f32 v[4:5], v[4:5], v[84:85]
	v_pk_mul_f32 v[2:3], v[2:3], v[78:79]
	v_pk_mul_f32 v[0:1], v[0:1], v[76:77]
	s_and_b64 vcc, exec, s[54:55]
	s_cbranch_vccz .Lres44_rmw

;     __device__ __forceinline__ void operator()(const f32x4 (&acc)[2][2][4][2], const pg8::Unit& u, int wr, int wc, int fr, int fq) const {
;     ...
;                 for (int bj = 0; bj < 2; ++bj)
; #pragma unroll
;                     for (int n = 0; n < 2; ++n) {
;                         const f32x4 v = gv[bj][n] * acc[ai][bj][m][n]; float* pe = rowp + bj * 128 + n * 16;
;                         if (split) *(f32x4*)(pe + pboff) = v;
;                         else { f32x4* p = (f32x4*)pe; *p = *p + v; }
	global_store_dwordx4 v150, v[140:143], s[4:5]
	global_store_dwordx4 v150, v[136:139], s[4:5] offset:64
	global_store_dwordx4 v150, v[132:135], s[4:5] offset:512
	global_store_dwordx4 v150, v[128:131], s[4:5] offset:576
	global_store_dwordx4 v151, v[124:127], s[4:5]
	global_store_dwordx4 v151, v[120:123], s[4:5] offset:64
	global_store_dwordx4 v151, v[116:119], s[4:5] offset:512
	global_store_dwordx4 v151, v[112:115], s[4:5] offset:576
	global_store_dwordx4 v152, v[108:111], s[4:5]
	global_store_dwordx4 v152, v[104:107], s[4:5] offset:64
	global_store_dwordx4 v152, v[96:99], s[4:5] offset:512
	global_store_dwordx4 v152, v[88:91], s[4:5] offset:576
	global_store_dwordx4 v153, v[80:83], s[4:5]
	global_store_dwordx4 v153, v[72:75], s[4:5] offset:64
	global_store_dwordx4 v153, v[68:71], s[4:5] offset:512
	global_store_dwordx4 v153, v[64:67], s[4:5] offset:576
	global_store_dwordx4 v154, v[60:63], s[4:5]
	global_store_dwordx4 v154, v[56:59], s[4:5] offset:64
	global_store_dwordx4 v154, v[52:55], s[4:5] offset:512
	global_store_dwordx4 v154, v[48:51], s[4:5] offset:576
	global_store_dwordx4 v155, v[44:47], s[4:5]
	global_store_dwordx4 v155, v[40:43], s[4:5] offset:64
	global_store_dwordx4 v155, v[36:39], s[4:5] offset:512
	global_store_dwordx4 v155, v[32:35], s[4:5] offset:576
	global_store_dwordx4 v156, v[28:31], s[4:5]
	global_store_dwordx4 v156, v[24:27], s[4:5] offset:64
	global_store_dwordx4 v156, v[20:23], s[4:5] offset:512
	global_store_dwordx4 v156, v[16:19], s[4:5] offset:576
	global_store_dwordx4 v157, v[12:15], s[4:5]
	global_store_dwordx4 v157, v[8:11], s[4:5] offset:64
	global_store_dwordx4 v157, v[4:7], s[4:5] offset:512
	global_store_dwordx4 v157, v[0:3], s[4:5] offset:576
	s_branch .Lres44_done

; #define PG8_BAR __builtin_amdgcn_s_barrier()
; template <class Epi, class Sched, bool ALIGN_EPI = false, bool SP2 = false>
; __device__ __forceinline__ void gemm_phase(PG8_LAS unsigned char* lds, const Gemm g, const Sched& S, const Epi& E) {
;     ...
;         if constexpr (ALIGN_EPI) { if (wr == 0) PG8_BAR; }
;         if constexpr (!Epi::AFTER_DRAIN) { E(acc, cur, wr, wc, fr, fq); S.done(cur); }
;         if (!has_next) break;
; #pragma unroll
;         for (int a = 0; a < 2; ++a)
; #pragma unroll
;             for (int b = 0; b < 2; ++b)
; #pragma unroll
;                 for (int m = 0; m < 4; ++m)
; #pragma unroll
;                     for (int n = 0; n < 2; ++n) acc[a][b][m][n] = (f32x4){0.f, 0.f, 0.f, 0.f};
;         cur = nxt; cA = nA; cB = nB; ++ui;
;         if constexpr (ALIGN_EPI) { if (wr == 1) PG8_BAR; }
;     __device__ __forceinline__ void operator()(const f32x4 (&acc)[2][2][4][2], const pg8::Unit& u, int wr, int wc, int fr, int fq) const {
;     ...
;                         const f32x4 v = gv[bj][n] * acc[ai][bj][m][n]; float* pe = rowp + bj * 128 + n * 16;
;                         if (split) *(f32x4*)(pe + pboff) = v;
;                         else { f32x4* p = (f32x4*)pe; *p = *p + v; }
.Lres44_done:
	s_and_b64 vcc, exec, s[38:39]
	s_mov_b64 s[2:3], -1
	s_cbranch_vccnz .LBB0_896
.LBB0_1041:
	s_andn2_b64 vcc, exec, s[42:43]
	s_cbranch_vccnz .LBB0_895
	s_barrier
	s_branch .LBB0_895
